# GEMM unit transitions: next unit's row-ss loads stay in flight during the epilogue (vmcnt(0)->vmcnt(8) at head, vmcnt(16) at latch)
# baseline (speedup 1.0000x reference)
; template <class Epi, bool ALIGN_EPI>
; __device__ __forceinline__ void gemm_phase(LAS unsigned char* lds, const Gemm g, const StaticOrder& S, const Epi& E) {
;     ...
;     for (;;) {
;         const bool has_next = S.next(ui + 1, nxt);
;     ...
;         cur = nxt; cA = nA; cB = nB; ++ui;
; #pragma unroll
;         for (int i_ = 0; i_ < 8; ++i_) rsv[i_] = rsn[i_];
.LBB0_244:
	s_waitcnt vmcnt(16)
	s_andn2_b64 vcc, exec, s[4:5]
	v_mov_b32_e32 v144, v157
	v_mov_b32_e32 v145, v158
	v_mov_b32_e32 v146, v159
	v_mov_b32_e32 v148, v160
	v_mov_b32_e32 v150, v161
	v_mov_b32_e32 v152, v162
	v_mov_b32_e32 v165, v163
	v_mov_b32_e32 v166, v164
	s_mov_b32 s66, s44
	s_mov_b32 s52, s46
	s_mov_b64 s[8:9], s[50:51]
	s_mov_b64 s[6:7], s[48:49]
	s_cbranch_vccz .LBB0_260

; __device__ __forceinline__ unsigned cvt_pk_bf16(float lo, float hi) { unsigned r; asm volatile("v_cvt_pk_bf16_f32 %0, %1, %2" : "=v"(r) : "v"(lo), "v"(hi)); return r; }
;     __device__ __forceinline__ void operator()(const f32x4 (&acc)[2][2][4][2], const Unit& u, int wr, int wc, int fr, int fq, int, const float (&rsv_)[8]) const {
;         bf16_t* base; int ldc, pnl; bool act2 = false;
;         if (u.pn < pn1) { base = O0; ldc = ld0; pnl = u.pn; act2 = true; } else if (u.pn < pn2) { base = O1; ldc = ld1; pnl = u.pn - pn1; } else { base = O2; ldc = ld2; pnl = u.pn - pn2; }
;         const int row0 = u.pm * BM + wr * 64 + fr; const int col0 = pnl * BM + wc * 32 + 8 * fq;
;         float rsv[2][4];
; #pragma unroll
;         for (int ai = 0; ai < 2; ++ai)
; #pragma unroll
;             for (int m = 0; m < 4; ++m) rsv[ai][m] = ss ? rsqrtf(rsv_[ai * 4 + m] * (1.f / 2048.f) + EPS) : 1.f;
; #pragma unroll
;         for (int ai = 0; ai < 2; ++ai)
; #pragma unroll
;             for (int m = 0; m < 4; ++m) { bf16_t* rowp = base + (size_t)(row0 + ai * HALF + m * 16) * ldc + col0;
;                 const float rs = rsv[ai][m];
; #pragma unroll
;                 for (int bj = 0; bj < 2; ++bj) { f32x4 v0 = acc[ai][bj][m][0] * rs, v1 = acc[ai][bj][m][1] * rs;
;                     if (ACT == 1) {
; #pragma unroll
;                         for (int j = 0; j < 4; ++j) { const float a = fmaxf(v0[j], 0.f), b = fmaxf(v1[j], 0.f); v0[j] = a * a; v1[j] = b * b; } }
;                     if (ACT == 2) { if (act2) {
; #pragma unroll
;                         for (int j = 0; j < 4; ++j) { float x = v0[j]; float z = 0.7978845608028654f * (x + 0.044715f * x * x * x); v0[j] = x / (1.f + __expf(-2.f * z));
;                                                       x = v1[j]; z = 0.7978845608028654f * (x + 0.044715f * x * x * x); v1[j] = x / (1.f + __expf(-2.f * z)); } } }
;                     u32x4 w; w.x = cvt_pk_bf16(v0[0], v0[1]); w.y = cvt_pk_bf16(v0[2], v0[3]); w.z = cvt_pk_bf16(v1[0], v1[1]); w.w = cvt_pk_bf16(v1[2], v1[3]);
;                     { u32x4* dp_ = (u32x4*)(rowp + bj * HALF); asm volatile("global_store_dwordx4 %0, %1, off sc1\n\ts_nop 1" :: "v"(dp_), "v"(w) : "memory"); } } }
.LBB0_257:
	s_waitcnt vmcnt(8)
	v_fmamk_f32 v166, v166, 0x3a000000, v156
	v_mul_f32_e32 v167, 0x4b800000, v166
	v_cmp_gt_f32_e32 vcc, s65, v166
	v_fmamk_f32 v165, v165, 0x3a000000, v156
	v_cmp_gt_f32_e64 s[4:5], s65, v165
	v_cndmask_b32_e32 v166, v166, v167, vcc
	v_rsq_f32_e32 v166, v166
	v_mul_f32_e32 v167, 0x4b800000, v165
	v_cndmask_b32_e64 v165, v165, v167, s[4:5]
	v_fmamk_f32 v152, v152, 0x3a000000, v156
	v_mul_f32_e32 v167, 0x45800000, v166
	v_cndmask_b32_e32 v166, v166, v167, vcc
	v_mul_f32_e32 v168, 0x4b800000, v152
	v_cmp_gt_f32_e32 vcc, s65, v152
	v_rsq_f32_e32 v165, v165
	v_fmamk_f32 v150, v150, 0x3a000000, v156
	v_cndmask_b32_e32 v152, v152, v168, vcc
	v_rsq_f32_e32 v152, v152
	v_mul_f32_e32 v167, 0x45800000, v165
	v_mul_f32_e32 v168, 0x4b800000, v150
	v_cmp_gt_f32_e64 s[8:9], s65, v150
	v_fmamk_f32 v148, v148, 0x3a000000, v156
	v_fmamk_f32 v146, v146, 0x3a000000, v156
	v_cndmask_b32_e64 v150, v150, v168, s[8:9]
	v_cndmask_b32_e64 v168, v165, v167, s[4:5]
	v_mul_f32_e32 v165, 0x45800000, v152
	v_cndmask_b32_e32 v170, v152, v165, vcc
	v_mul_f32_e32 v165, 0x4b800000, v148
	v_cmp_gt_f32_e32 vcc, s65, v148
	v_rsq_f32_e32 v150, v150
	v_cmp_gt_f32_e64 s[4:5], s65, v146
	v_cndmask_b32_e32 v148, v148, v165, vcc
	v_rsq_f32_e32 v148, v148
	v_mul_f32_e32 v152, 0x45800000, v150
	v_mul_f32_e32 v165, 0x4b800000, v146
	v_cndmask_b32_e64 v172, v150, v152, s[8:9]
	v_mul_f32_e32 v150, 0x45800000, v148
	v_fmamk_f32 v145, v145, 0x3a000000, v156
	v_cndmask_b32_e64 v146, v146, v165, s[4:5]
	v_cndmask_b32_e32 v152, v148, v150, vcc
	v_mul_f32_e32 v150, 0x4b800000, v145
	v_cmp_gt_f32_e32 vcc, s65, v145
	v_fmamk_f32 v144, v144, 0x3a000000, v156
	v_rsq_f32_e32 v146, v146
	v_cndmask_b32_e32 v145, v145, v150, vcc
	v_mul_f32_e32 v150, 0x4b800000, v144
	v_cmp_gt_f32_e64 s[8:9], s65, v144
	v_rsq_f32_e32 v145, v145
	v_mul_f32_e32 v148, 0x45800000, v146
	v_cndmask_b32_e64 v144, v144, v150, s[8:9]
	v_rsq_f32_e32 v144, v144
	v_cndmask_b32_e64 v150, v146, v148, s[4:5]
	v_mul_f32_e32 v146, 0x45800000, v145
	v_cndmask_b32_e32 v148, v145, v146, vcc
	v_mul_f32_e32 v145, 0x45800000, v144
	v_cndmask_b32_e64 v146, v144, v145, s[8:9]
	v_lshl_add_u32 v174, s52, 8, v147
	v_lshl_or_b32 v144, s66, 8, v151
	v_ashrrev_i32_e32 v145, 31, v144
	v_ashrrev_i32_e32 v175, 31, v174
	v_lshl_add_u64 v[176:177], v[144:145], 1, s[18:19]
	v_lshlrev_b64 v[144:145], 12, v[174:175]
	v_pk_mul_f32 v[126:127], v[166:167], v[126:127] op_sel_hi:[0,1]
	v_pk_mul_f32 v[124:125], v[166:167], v[124:125] op_sel_hi:[0,1]
	v_pk_mul_f32 v[178:179], v[166:167], v[122:123] op_sel_hi:[0,1]
	v_pk_mul_f32 v[122:123], v[166:167], v[120:121] op_sel_hi:[0,1]
	v_cvt_pk_bf16_f32 v120, v124, v125
	v_cvt_pk_bf16_f32 v121, v126, v127
	v_lshl_add_u64 v[144:145], v[176:177], 0, v[144:145]
	v_cvt_pk_bf16_f32 v122, v122, v123
	v_cvt_pk_bf16_f32 v123, v178, v179
	v_pk_mul_f32 v[116:117], v[166:167], v[116:117] op_sel_hi:[0,1]
	global_store_dwordx4 v[144:145], v[120:123], off sc1
	s_nop 1
	v_pk_mul_f32 v[120:121], v[166:167], v[114:115] op_sel_hi:[0,1]
	v_pk_mul_f32 v[114:115], v[166:167], v[112:113] op_sel_hi:[0,1]
	v_cvt_pk_bf16_f32 v112, v116, v117
	v_pk_mul_f32 v[118:119], v[166:167], v[118:119] op_sel_hi:[0,1]
	v_cvt_pk_bf16_f32 v113, v118, v119
	v_cvt_pk_bf16_f32 v114, v114, v115
	v_cvt_pk_bf16_f32 v115, v120, v121
	v_lshl_add_u64 v[116:117], v[144:145], 0, s[24:25]
	global_store_dwordx4 v[116:117], v[112:115], off sc1
	s_nop 1
	v_or_b32_e32 v112, 16, v174
	v_ashrrev_i32_e32 v113, 31, v112
	v_lshlrev_b64 v[112:113], 12, v[112:113]
	v_pk_mul_f32 v[110:111], v[168:169], v[110:111] op_sel_hi:[0,1]
	v_pk_mul_f32 v[108:109], v[168:169], v[108:109] op_sel_hi:[0,1]
	v_pk_mul_f32 v[114:115], v[168:169], v[106:107] op_sel_hi:[0,1]
	v_pk_mul_f32 v[106:107], v[168:169], v[104:105] op_sel_hi:[0,1]
	v_cvt_pk_bf16_f32 v104, v108, v109
	v_cvt_pk_bf16_f32 v105, v110, v111
	v_lshl_add_u64 v[112:113], v[176:177], 0, v[112:113]
	v_cvt_pk_bf16_f32 v106, v106, v107
	v_cvt_pk_bf16_f32 v107, v114, v115
	v_pk_mul_f32 v[100:101], v[168:169], v[100:101] op_sel_hi:[0,1]
	global_store_dwordx4 v[112:113], v[104:107], off sc1
	s_nop 1
	v_pk_mul_f32 v[104:105], v[168:169], v[98:99] op_sel_hi:[0,1]
	v_pk_mul_f32 v[98:99], v[168:169], v[96:97] op_sel_hi:[0,1]
	v_cvt_pk_bf16_f32 v96, v100, v101
	v_pk_mul_f32 v[102:103], v[168:169], v[102:103] op_sel_hi:[0,1]
	v_cvt_pk_bf16_f32 v97, v102, v103
	v_cvt_pk_bf16_f32 v98, v98, v99
	v_cvt_pk_bf16_f32 v99, v104, v105
	v_lshl_add_u64 v[100:101], v[112:113], 0, s[24:25]
	global_store_dwordx4 v[100:101], v[96:99], off sc1
	s_nop 1
	v_or_b32_e32 v96, 32, v174
	v_ashrrev_i32_e32 v97, 31, v96
	v_lshlrev_b64 v[96:97], 12, v[96:97]
	v_pk_mul_f32 v[94:95], v[170:171], v[94:95] op_sel_hi:[0,1]
	v_pk_mul_f32 v[92:93], v[170:171], v[92:93] op_sel_hi:[0,1]
	v_pk_mul_f32 v[98:99], v[170:171], v[90:91] op_sel_hi:[0,1]
	v_pk_mul_f32 v[90:91], v[170:171], v[88:89] op_sel_hi:[0,1]
	v_cvt_pk_bf16_f32 v88, v92, v93
	v_cvt_pk_bf16_f32 v89, v94, v95
	v_lshl_add_u64 v[96:97], v[176:177], 0, v[96:97]
	v_cvt_pk_bf16_f32 v90, v90, v91
	v_cvt_pk_bf16_f32 v91, v98, v99
	v_pk_mul_f32 v[84:85], v[170:171], v[84:85] op_sel_hi:[0,1]
	global_store_dwordx4 v[96:97], v[88:91], off sc1
	s_nop 1
	v_pk_mul_f32 v[88:89], v[170:171], v[82:83] op_sel_hi:[0,1]
	v_pk_mul_f32 v[82:83], v[170:171], v[80:81] op_sel_hi:[0,1]
	v_cvt_pk_bf16_f32 v80, v84, v85
; __device__ __forceinline__ unsigned cvt_pk_bf16(float lo, float hi) { unsigned r; asm volatile("v_cvt_pk_bf16_f32 %0, %1, %2" : "=v"(r) : "v"(lo), "v"(hi)); return r; }
;     __device__ __forceinline__ void operator()(const f32x4 (&acc)[2][2][4][2], const Unit& u, int wr, int wc, int fr, int fq, int, const float (&rsv_)[8]) const {
;     ...
;             for (int m = 0; m < 4; ++m) { bf16_t* rowp = base + (size_t)(row0 + ai * HALF + m * 16) * ldc + col0;
;                 const float rs = rsv[ai][m];
; #pragma unroll
;                 for (int bj = 0; bj < 2; ++bj) { f32x4 v0 = acc[ai][bj][m][0] * rs, v1 = acc[ai][bj][m][1] * rs;
;                     if (ACT == 1) {
; #pragma unroll
;                         for (int j = 0; j < 4; ++j) { const float a = fmaxf(v0[j], 0.f), b = fmaxf(v1[j], 0.f); v0[j] = a * a; v1[j] = b * b; } }
;                     if (ACT == 2) { if (act2) {
; #pragma unroll
;                         for (int j = 0; j < 4; ++j) { float x = v0[j]; float z = 0.7978845608028654f * (x + 0.044715f * x * x * x); v0[j] = x / (1.f + __expf(-2.f * z));
;                                                       x = v1[j]; z = 0.7978845608028654f * (x + 0.044715f * x * x * x); v1[j] = x / (1.f + __expf(-2.f * z)); } } }
;                     u32x4 w; w.x = cvt_pk_bf16(v0[0], v0[1]); w.y = cvt_pk_bf16(v0[2], v0[3]); w.z = cvt_pk_bf16(v1[0], v1[1]); w.w = cvt_pk_bf16(v1[2], v1[3]);
;                     { u32x4* dp_ = (u32x4*)(rowp + bj * HALF); asm volatile("global_store_dwordx4 %0, %1, off sc1\n\ts_nop 1" :: "v"(dp_), "v"(w) : "memory"); } } }
	v_pk_mul_f32 v[86:87], v[170:171], v[86:87] op_sel_hi:[0,1]
	v_cvt_pk_bf16_f32 v81, v86, v87
	v_cvt_pk_bf16_f32 v82, v82, v83
	v_cvt_pk_bf16_f32 v83, v88, v89
	v_lshl_add_u64 v[84:85], v[96:97], 0, s[24:25]
	global_store_dwordx4 v[84:85], v[80:83], off sc1
	s_nop 1
	v_or_b32_e32 v80, 48, v174
	v_ashrrev_i32_e32 v81, 31, v80
	v_lshlrev_b64 v[80:81], 12, v[80:81]
	v_pk_mul_f32 v[78:79], v[172:173], v[78:79] op_sel_hi:[0,1]
	v_pk_mul_f32 v[76:77], v[172:173], v[76:77] op_sel_hi:[0,1]
	v_pk_mul_f32 v[82:83], v[172:173], v[74:75] op_sel_hi:[0,1]
	v_pk_mul_f32 v[74:75], v[172:173], v[72:73] op_sel_hi:[0,1]
	v_cvt_pk_bf16_f32 v72, v76, v77
	v_cvt_pk_bf16_f32 v73, v78, v79
	v_lshl_add_u64 v[80:81], v[176:177], 0, v[80:81]
	v_cvt_pk_bf16_f32 v74, v74, v75
	v_cvt_pk_bf16_f32 v75, v82, v83
	v_pk_mul_f32 v[70:71], v[172:173], v[70:71] op_sel_hi:[0,1]
	global_store_dwordx4 v[80:81], v[72:75], off sc1
	s_nop 1
	v_pk_mul_f32 v[72:73], v[172:173], v[66:67] op_sel_hi:[0,1]
	v_pk_mul_f32 v[66:67], v[172:173], v[64:65] op_sel_hi:[0,1]
	v_pk_mul_f32 v[68:69], v[172:173], v[68:69] op_sel_hi:[0,1]
	v_cvt_pk_bf16_f32 v64, v68, v69
	v_cvt_pk_bf16_f32 v65, v70, v71
	v_cvt_pk_bf16_f32 v66, v66, v67
	v_cvt_pk_bf16_f32 v67, v72, v73
	v_lshl_add_u64 v[68:69], v[80:81], 0, s[24:25]
	global_store_dwordx4 v[68:69], v[64:67], off sc1
	s_nop 1
	v_pk_mul_f32 v[62:63], v[152:153], v[62:63] op_sel_hi:[0,1]
	v_pk_mul_f32 v[60:61], v[152:153], v[60:61] op_sel_hi:[0,1]
	v_pk_mul_f32 v[66:67], v[152:153], v[58:59] op_sel_hi:[0,1]
	v_pk_mul_f32 v[58:59], v[152:153], v[56:57] op_sel_hi:[0,1]
	v_cvt_pk_bf16_f32 v56, v60, v61
	v_cvt_pk_bf16_f32 v57, v62, v63
	v_lshl_add_u64 v[64:65], v[144:145], 0, s[14:15]
	v_cvt_pk_bf16_f32 v58, v58, v59
	v_cvt_pk_bf16_f32 v59, v66, v67
	v_pk_mul_f32 v[54:55], v[152:153], v[54:55] op_sel_hi:[0,1]
	global_store_dwordx4 v[64:65], v[56:59], off sc1
	s_nop 1
	v_pk_mul_f32 v[56:57], v[152:153], v[46:47] op_sel_hi:[0,1]
	v_pk_mul_f32 v[46:47], v[152:153], v[44:45] op_sel_hi:[0,1]
	v_pk_mul_f32 v[52:53], v[152:153], v[52:53] op_sel_hi:[0,1]
	v_cvt_pk_bf16_f32 v44, v52, v53
	v_cvt_pk_bf16_f32 v45, v54, v55
	v_cvt_pk_bf16_f32 v46, v46, v47
	v_cvt_pk_bf16_f32 v47, v56, v57
	v_lshl_add_u64 v[52:53], v[144:145], 0, s[26:27]
	global_store_dwordx4 v[52:53], v[44:47], off sc1
	s_nop 1
	v_pk_mul_f32 v[46:47], v[150:151], v[50:51] op_sel_hi:[0,1]
	v_pk_mul_f32 v[48:49], v[150:151], v[48:49] op_sel_hi:[0,1]
	v_pk_mul_f32 v[50:51], v[150:151], v[42:43] op_sel_hi:[0,1]
	v_pk_mul_f32 v[42:43], v[150:151], v[40:41] op_sel_hi:[0,1]
	v_cvt_pk_bf16_f32 v40, v48, v49
	v_cvt_pk_bf16_f32 v41, v46, v47
	v_lshl_add_u64 v[44:45], v[144:145], 0, s[28:29]
	v_cvt_pk_bf16_f32 v42, v42, v43
	v_cvt_pk_bf16_f32 v43, v50, v51
	v_pk_mul_f32 v[38:39], v[150:151], v[38:39] op_sel_hi:[0,1]
	global_store_dwordx4 v[44:45], v[40:43], off sc1
	s_nop 1
	v_pk_mul_f32 v[40:41], v[150:151], v[30:31] op_sel_hi:[0,1]
	v_pk_mul_f32 v[30:31], v[150:151], v[28:29] op_sel_hi:[0,1]
	v_pk_mul_f32 v[36:37], v[150:151], v[36:37] op_sel_hi:[0,1]
	v_cvt_pk_bf16_f32 v28, v36, v37
	v_cvt_pk_bf16_f32 v29, v38, v39
	v_cvt_pk_bf16_f32 v30, v30, v31
	v_cvt_pk_bf16_f32 v31, v40, v41
	v_lshl_add_u64 v[36:37], v[144:145], 0, s[30:31]
	global_store_dwordx4 v[36:37], v[28:31], off sc1
	s_nop 1
	v_pk_mul_f32 v[30:31], v[148:149], v[34:35] op_sel_hi:[0,1]
	v_pk_mul_f32 v[32:33], v[148:149], v[32:33] op_sel_hi:[0,1]
	v_pk_mul_f32 v[34:35], v[148:149], v[26:27] op_sel_hi:[0,1]
	v_pk_mul_f32 v[26:27], v[148:149], v[24:25] op_sel_hi:[0,1]
	v_cvt_pk_bf16_f32 v24, v32, v33
	v_cvt_pk_bf16_f32 v25, v30, v31
	v_lshl_add_u64 v[28:29], v[144:145], 0, s[34:35]
	v_cvt_pk_bf16_f32 v26, v26, v27
	v_cvt_pk_bf16_f32 v27, v34, v35
	v_pk_mul_f32 v[22:23], v[148:149], v[22:23] op_sel_hi:[0,1]
	global_store_dwordx4 v[28:29], v[24:27], off sc1
	s_nop 1
	v_pk_mul_f32 v[24:25], v[148:149], v[14:15] op_sel_hi:[0,1]
	v_pk_mul_f32 v[14:15], v[148:149], v[12:13] op_sel_hi:[0,1]
	v_pk_mul_f32 v[20:21], v[148:149], v[20:21] op_sel_hi:[0,1]
	v_cvt_pk_bf16_f32 v12, v20, v21
	v_cvt_pk_bf16_f32 v13, v22, v23
	v_cvt_pk_bf16_f32 v14, v14, v15
	v_cvt_pk_bf16_f32 v15, v24, v25
	v_lshl_add_u64 v[20:21], v[144:145], 0, s[36:37]
	global_store_dwordx4 v[20:21], v[12:15], off sc1
	s_nop 1
	v_pk_mul_f32 v[14:15], v[146:147], v[18:19] op_sel_hi:[0,1]
	v_pk_mul_f32 v[16:17], v[146:147], v[16:17] op_sel_hi:[0,1]
	v_pk_mul_f32 v[18:19], v[146:147], v[10:11] op_sel_hi:[0,1]
	v_pk_mul_f32 v[10:11], v[146:147], v[8:9] op_sel_hi:[0,1]
	v_cvt_pk_bf16_f32 v8, v16, v17
	v_cvt_pk_bf16_f32 v9, v14, v15
	v_lshl_add_u64 v[12:13], v[144:145], 0, s[40:41]
	v_cvt_pk_bf16_f32 v10, v10, v11
	v_cvt_pk_bf16_f32 v11, v18, v19
	v_pk_mul_f32 v[4:5], v[146:147], v[4:5] op_sel_hi:[0,1]
	global_store_dwordx4 v[12:13], v[8:11], off sc1
	s_nop 1
	v_pk_mul_f32 v[8:9], v[146:147], v[2:3] op_sel_hi:[0,1]
	v_pk_mul_f32 v[2:3], v[146:147], v[0:1] op_sel_hi:[0,1]
	v_pk_mul_f32 v[6:7], v[146:147], v[6:7] op_sel_hi:[0,1]
	v_cvt_pk_bf16_f32 v0, v4, v5
	v_cvt_pk_bf16_f32 v1, v6, v7
	v_cvt_pk_bf16_f32 v2, v2, v3
	v_cvt_pk_bf16_f32 v3, v8, v9
	v_lshl_add_u64 v[4:5], v[144:145], 0, s[42:43]
	global_store_dwordx4 v[4:5], v[0:3], off sc1
	s_nop 1
	s_and_b64 vcc, exec, s[6:7]
	s_mov_b64 s[4:5], -1
	s_cbranch_vccnz .LBB0_244
	s_andn2_b64 vcc, exec, s[16:17]
	s_cbranch_vccnz .LBB0_243
	s_barrier
	s_branch .LBB0_243

; template <class Epi, bool ALIGN_EPI>
; __device__ __forceinline__ void gemm_phase(LAS unsigned char* lds, const Gemm g, const StaticOrder& S, const Epi& E) {
;     ...
;         cur = nxt; cA = nA; cB = nB; ++ui;
; #pragma unroll
;         for (int i_ = 0; i_ < 8; ++i_) rsv[i_] = rsn[i_];
.LBB0_918:
	s_waitcnt vmcnt(16)
	s_andn2_b64 vcc, exec, s[4:5]
	v_mov_b32_e32 v144, v158
	v_mov_b32_e32 v145, v159
	v_mov_b32_e32 v146, v160
	v_mov_b32_e32 v148, v161
	v_mov_b32_e32 v150, v162
	v_mov_b32_e32 v152, v163
	v_mov_b32_e32 v154, v164
	v_mov_b32_e32 v166, v165
	s_mov_b32 s66, s44
	s_mov_b32 s52, s46
	s_mov_b64 s[8:9], s[50:51]
	s_mov_b64 s[6:7], s[48:49]
	s_cbranch_vccz .LBB0_934

; __device__ __forceinline__ unsigned cvt_pk_bf16(float lo, float hi) { unsigned r; asm volatile("v_cvt_pk_bf16_f32 %0, %1, %2" : "=v"(r) : "v"(lo), "v"(hi)); return r; }
;     __device__ __forceinline__ void operator()(const f32x4 (&acc)[2][2][4][2], const Unit& u, int wr, int wc, int fr, int fq, int, const float (&rsv_)[8]) const {
;         bf16_t* base; int ldc, pnl; bool act2 = false;
;         if (u.pn < pn1) { base = O0; ldc = ld0; pnl = u.pn; act2 = true; } else if (u.pn < pn2) { base = O1; ldc = ld1; pnl = u.pn - pn1; } else { base = O2; ldc = ld2; pnl = u.pn - pn2; }
;         const int row0 = u.pm * BM + wr * 64 + fr; const int col0 = pnl * BM + wc * 32 + 8 * fq;
;         float rsv[2][4];
; #pragma unroll
;         for (int ai = 0; ai < 2; ++ai)
; #pragma unroll
;             for (int m = 0; m < 4; ++m) rsv[ai][m] = ss ? rsqrtf(rsv_[ai * 4 + m] * (1.f / 2048.f) + EPS) : 1.f;
; #pragma unroll
;         for (int ai = 0; ai < 2; ++ai)
; #pragma unroll
;             for (int m = 0; m < 4; ++m) { bf16_t* rowp = base + (size_t)(row0 + ai * HALF + m * 16) * ldc + col0;
;                 const float rs = rsv[ai][m];
; #pragma unroll
;                 for (int bj = 0; bj < 2; ++bj) { f32x4 v0 = acc[ai][bj][m][0] * rs, v1 = acc[ai][bj][m][1] * rs;
;                     if (ACT == 1) {
; #pragma unroll
;                         for (int j = 0; j < 4; ++j) { const float a = fmaxf(v0[j], 0.f), b = fmaxf(v1[j], 0.f); v0[j] = a * a; v1[j] = b * b; } }
;                     if (ACT == 2) { if (act2) {
; #pragma unroll
;                         for (int j = 0; j < 4; ++j) { float x = v0[j]; float z = 0.7978845608028654f * (x + 0.044715f * x * x * x); v0[j] = x / (1.f + __expf(-2.f * z));
;                                                       x = v1[j]; z = 0.7978845608028654f * (x + 0.044715f * x * x * x); v1[j] = x / (1.f + __expf(-2.f * z)); } } }
;                     u32x4 w; w.x = cvt_pk_bf16(v0[0], v0[1]); w.y = cvt_pk_bf16(v0[2], v0[3]); w.z = cvt_pk_bf16(v1[0], v1[1]); w.w = cvt_pk_bf16(v1[2], v1[3]);
;                     { u32x4* dp_ = (u32x4*)(rowp + bj * HALF); asm volatile("global_store_dwordx4 %0, %1, off sc1\n\ts_nop 1" :: "v"(dp_), "v"(w) : "memory"); } } }
.LBB0_931:
	s_waitcnt vmcnt(8)
	v_fmamk_f32 v166, v166, 0x3a000000, v157
	v_mul_f32_e32 v167, 0x4b800000, v166
	v_cmp_gt_f32_e32 vcc, s65, v166
	v_fmamk_f32 v154, v154, 0x3a000000, v157
	v_cmp_gt_f32_e64 s[4:5], s65, v154
	v_cndmask_b32_e32 v166, v166, v167, vcc
	v_rsq_f32_e32 v166, v166
	v_mul_f32_e32 v167, 0x4b800000, v154
	v_cndmask_b32_e64 v154, v154, v167, s[4:5]
	v_fmamk_f32 v152, v152, 0x3a000000, v157
	v_mul_f32_e32 v167, 0x45800000, v166
	v_cndmask_b32_e32 v166, v166, v167, vcc
	v_mul_f32_e32 v168, 0x4b800000, v152
	v_cmp_gt_f32_e32 vcc, s65, v152
	v_rsq_f32_e32 v154, v154
	v_fmamk_f32 v150, v150, 0x3a000000, v157
	v_cndmask_b32_e32 v152, v152, v168, vcc
	v_rsq_f32_e32 v152, v152
	v_mul_f32_e32 v167, 0x45800000, v154
	v_mul_f32_e32 v168, 0x4b800000, v150
	v_cmp_gt_f32_e64 s[8:9], s65, v150
	v_fmamk_f32 v148, v148, 0x3a000000, v157
	v_fmamk_f32 v146, v146, 0x3a000000, v157
	v_cndmask_b32_e64 v150, v150, v168, s[8:9]
	v_cndmask_b32_e64 v168, v154, v167, s[4:5]
	v_mul_f32_e32 v154, 0x45800000, v152
	v_cndmask_b32_e32 v170, v152, v154, vcc
	v_mul_f32_e32 v154, 0x4b800000, v148
	v_cmp_gt_f32_e32 vcc, s65, v148
	v_rsq_f32_e32 v150, v150
	v_cmp_gt_f32_e64 s[4:5], s65, v146
	v_cndmask_b32_e32 v148, v148, v154, vcc
	v_rsq_f32_e32 v148, v148
	v_mul_f32_e32 v152, 0x45800000, v150
	v_mul_f32_e32 v154, 0x4b800000, v146
	v_cndmask_b32_e64 v146, v146, v154, s[4:5]
	v_cndmask_b32_e64 v154, v150, v152, s[8:9]
	v_mul_f32_e32 v150, 0x45800000, v148
	v_fmamk_f32 v145, v145, 0x3a000000, v157
	v_cndmask_b32_e32 v152, v148, v150, vcc
	v_mul_f32_e32 v150, 0x4b800000, v145
	v_cmp_gt_f32_e32 vcc, s65, v145
	v_fmamk_f32 v144, v144, 0x3a000000, v157
	v_rsq_f32_e32 v146, v146
	v_cndmask_b32_e32 v145, v145, v150, vcc
	v_mul_f32_e32 v150, 0x4b800000, v144
	v_cmp_gt_f32_e64 s[8:9], s65, v144
	v_rsq_f32_e32 v145, v145
	v_mul_f32_e32 v148, 0x45800000, v146
	v_cndmask_b32_e64 v144, v144, v150, s[8:9]
	v_rsq_f32_e32 v144, v144
	v_cndmask_b32_e64 v150, v146, v148, s[4:5]
	v_mul_f32_e32 v146, 0x45800000, v145
	v_pk_mul_f32 v[120:121], v[166:167], v[120:121] op_sel_hi:[0,1]
	v_cndmask_b32_e32 v148, v145, v146, vcc
	v_mul_f32_e32 v145, 0x45800000, v144
	v_pk_mul_f32 v[124:125], v[166:167], v[124:125] op_sel_hi:[0,1]
	v_pk_mul_f32 v[122:123], v[166:167], v[122:123] op_sel_hi:[0,1]
	v_max_f32_e32 v120, 0, v120
	v_cndmask_b32_e64 v146, v144, v145, s[8:9]
	v_lshl_add_u32 v172, s52, 8, v147
	v_lshl_or_b32 v144, s66, 8, v151
	v_pk_mul_f32 v[126:127], v[166:167], v[126:127] op_sel_hi:[0,1]
	v_mul_f32_e32 v167, v120, v120
	v_max_f32_e32 v120, 0, v125
	v_max_f32_e32 v121, 0, v121
	v_max_f32_e32 v122, 0, v122
	v_ashrrev_i32_e32 v145, 31, v144
	v_ashrrev_i32_e32 v173, 31, v172
	v_max_f32_e32 v124, 0, v124
	v_mul_f32_e32 v120, v120, v120
	v_mul_f32_e32 v125, v121, v121
	v_max_f32_e32 v121, 0, v126
	v_mul_f32_e32 v126, v122, v122
	v_max_f32_e32 v122, 0, v127
	v_max_f32_e32 v123, 0, v123
	v_pk_mul_f32 v[114:115], v[166:167], v[114:115] op_sel_hi:[0,1]
	v_pk_mul_f32 v[112:113], v[166:167], v[112:113] op_sel_hi:[0,1]
	v_lshl_add_u64 v[174:175], v[144:145], 1, s[16:17]
	v_lshlrev_b64 v[144:145], 14, v[172:173]
	v_mul_f32_e32 v124, v124, v124
	v_mul_f32_e32 v121, v121, v121
	v_mul_f32_e32 v122, v122, v122
	v_mul_f32_e32 v123, v123, v123
	v_cvt_pk_bf16_f32 v120, v124, v120
	v_pk_mul_f32 v[118:119], v[166:167], v[118:119] op_sel_hi:[0,1]
	v_pk_mul_f32 v[116:117], v[166:167], v[116:117] op_sel_hi:[0,1]
	v_max_f32_e32 v112, 0, v112
	v_max_f32_e32 v113, 0, v113
	v_max_f32_e32 v114, 0, v114
	v_lshl_add_u64 v[144:145], v[174:175], 0, v[144:145]
	v_cvt_pk_bf16_f32 v121, v121, v122
	v_cvt_pk_bf16_f32 v122, v167, v125
	v_cvt_pk_bf16_f32 v123, v126, v123
	v_max_f32_e32 v116, 0, v116
	global_store_dwordx4 v[144:145], v[120:123], off sc1
	s_nop 1
	v_mul_f32_e32 v120, v112, v112
	v_max_f32_e32 v112, 0, v117
	v_mul_f32_e32 v117, v113, v113
	v_max_f32_e32 v113, 0, v118
	v_mul_f32_e32 v118, v114, v114
	v_max_f32_e32 v114, 0, v119
	v_mul_f32_e32 v112, v112, v112
	v_mul_f32_e32 v113, v113, v113
	v_max_f32_e32 v115, 0, v115
	v_mul_f32_e32 v114, v114, v114
	v_pk_mul_f32 v[104:105], v[168:169], v[104:105] op_sel_hi:[0,1]
	v_mul_f32_e32 v116, v116, v116
	v_mul_f32_e32 v115, v115, v115
	v_cvt_pk_bf16_f32 v112, v116, v112
	v_cvt_pk_bf16_f32 v113, v113, v114
	v_cvt_pk_bf16_f32 v114, v120, v117
	v_pk_mul_f32 v[108:109], v[168:169], v[108:109] op_sel_hi:[0,1]
	v_pk_mul_f32 v[106:107], v[168:169], v[106:107] op_sel_hi:[0,1]
	v_max_f32_e32 v104, 0, v104
	v_cvt_pk_bf16_f32 v115, v118, v115
	v_lshl_add_u64 v[116:117], v[144:145], 0, s[22:23]
	global_store_dwordx4 v[116:117], v[112:115], off sc1
	s_nop 1
	v_or_b32_e32 v112, 16, v172
	v_pk_mul_f32 v[110:111], v[168:169], v[110:111] op_sel_hi:[0,1]
	v_mul_f32_e32 v114, v104, v104
	v_max_f32_e32 v104, 0, v109
	v_max_f32_e32 v105, 0, v105
	v_max_f32_e32 v106, 0, v106
	v_ashrrev_i32_e32 v113, 31, v112
	v_max_f32_e32 v108, 0, v108
	v_mul_f32_e32 v104, v104, v104
	v_mul_f32_e32 v109, v105, v105
	v_max_f32_e32 v105, 0, v110
	v_mul_f32_e32 v110, v106, v106
	v_max_f32_e32 v106, 0, v111
	v_max_f32_e32 v107, 0, v107
	v_pk_mul_f32 v[98:99], v[168:169], v[98:99] op_sel_hi:[0,1]
	v_pk_mul_f32 v[96:97], v[168:169], v[96:97] op_sel_hi:[0,1]
	v_lshlrev_b64 v[112:113], 14, v[112:113]
	v_mul_f32_e32 v108, v108, v108
	v_mul_f32_e32 v105, v105, v105
	v_mul_f32_e32 v106, v106, v106
	v_mul_f32_e32 v107, v107, v107
	v_cvt_pk_bf16_f32 v104, v108, v104
	v_pk_mul_f32 v[102:103], v[168:169], v[102:103] op_sel_hi:[0,1]
	v_pk_mul_f32 v[100:101], v[168:169], v[100:101] op_sel_hi:[0,1]
	v_max_f32_e32 v96, 0, v96
	v_max_f32_e32 v97, 0, v97
	v_max_f32_e32 v98, 0, v98
	v_lshl_add_u64 v[112:113], v[174:175], 0, v[112:113]
; __device__ __forceinline__ unsigned cvt_pk_bf16(float lo, float hi) { unsigned r; asm volatile("v_cvt_pk_bf16_f32 %0, %1, %2" : "=v"(r) : "v"(lo), "v"(hi)); return r; }
;     __device__ __forceinline__ void operator()(const f32x4 (&acc)[2][2][4][2], const Unit& u, int wr, int wc, int fr, int fq, int, const float (&rsv_)[8]) const {
;     ...
;             for (int m = 0; m < 4; ++m) { bf16_t* rowp = base + (size_t)(row0 + ai * HALF + m * 16) * ldc + col0;
;                 const float rs = rsv[ai][m];
; #pragma unroll
;                 for (int bj = 0; bj < 2; ++bj) { f32x4 v0 = acc[ai][bj][m][0] * rs, v1 = acc[ai][bj][m][1] * rs;
;                     if (ACT == 1) {
; #pragma unroll
;                         for (int j = 0; j < 4; ++j) { const float a = fmaxf(v0[j], 0.f), b = fmaxf(v1[j], 0.f); v0[j] = a * a; v1[j] = b * b; } }
;                     if (ACT == 2) { if (act2) {
; #pragma unroll
;                         for (int j = 0; j < 4; ++j) { float x = v0[j]; float z = 0.7978845608028654f * (x + 0.044715f * x * x * x); v0[j] = x / (1.f + __expf(-2.f * z));
;                                                       x = v1[j]; z = 0.7978845608028654f * (x + 0.044715f * x * x * x); v1[j] = x / (1.f + __expf(-2.f * z)); } } }
;                     u32x4 w; w.x = cvt_pk_bf16(v0[0], v0[1]); w.y = cvt_pk_bf16(v0[2], v0[3]); w.z = cvt_pk_bf16(v1[0], v1[1]); w.w = cvt_pk_bf16(v1[2], v1[3]);
;                     { u32x4* dp_ = (u32x4*)(rowp + bj * HALF); asm volatile("global_store_dwordx4 %0, %1, off sc1\n\ts_nop 1" :: "v"(dp_), "v"(w) : "memory"); } } }
	v_cvt_pk_bf16_f32 v105, v105, v106
	v_cvt_pk_bf16_f32 v106, v114, v109
	v_cvt_pk_bf16_f32 v107, v110, v107
	v_max_f32_e32 v100, 0, v100
	global_store_dwordx4 v[112:113], v[104:107], off sc1
	s_nop 1
	v_mul_f32_e32 v104, v96, v96
	v_max_f32_e32 v96, 0, v101
	v_mul_f32_e32 v101, v97, v97
	v_max_f32_e32 v97, 0, v102
	v_mul_f32_e32 v102, v98, v98
	v_max_f32_e32 v98, 0, v103
	v_mul_f32_e32 v96, v96, v96
	v_mul_f32_e32 v97, v97, v97
	v_max_f32_e32 v99, 0, v99
	v_mul_f32_e32 v98, v98, v98
	v_pk_mul_f32 v[88:89], v[170:171], v[88:89] op_sel_hi:[0,1]
	v_mul_f32_e32 v100, v100, v100
	v_mul_f32_e32 v99, v99, v99
	v_cvt_pk_bf16_f32 v96, v100, v96
	v_cvt_pk_bf16_f32 v97, v97, v98
	v_cvt_pk_bf16_f32 v98, v104, v101
	v_pk_mul_f32 v[92:93], v[170:171], v[92:93] op_sel_hi:[0,1]
	v_pk_mul_f32 v[90:91], v[170:171], v[90:91] op_sel_hi:[0,1]
	v_max_f32_e32 v88, 0, v88
	v_cvt_pk_bf16_f32 v99, v102, v99
	v_lshl_add_u64 v[100:101], v[112:113], 0, s[22:23]
	global_store_dwordx4 v[100:101], v[96:99], off sc1
	s_nop 1
	v_or_b32_e32 v96, 32, v172
	v_pk_mul_f32 v[94:95], v[170:171], v[94:95] op_sel_hi:[0,1]
	v_mul_f32_e32 v98, v88, v88
	v_max_f32_e32 v88, 0, v93
	v_max_f32_e32 v89, 0, v89
	v_max_f32_e32 v90, 0, v90
	v_ashrrev_i32_e32 v97, 31, v96
	v_max_f32_e32 v92, 0, v92
	v_mul_f32_e32 v88, v88, v88
	v_mul_f32_e32 v93, v89, v89
	v_max_f32_e32 v89, 0, v94
	v_mul_f32_e32 v94, v90, v90
	v_max_f32_e32 v90, 0, v95
	v_max_f32_e32 v91, 0, v91
	v_pk_mul_f32 v[82:83], v[170:171], v[82:83] op_sel_hi:[0,1]
	v_pk_mul_f32 v[80:81], v[170:171], v[80:81] op_sel_hi:[0,1]
	v_lshlrev_b64 v[96:97], 14, v[96:97]
	v_mul_f32_e32 v92, v92, v92
	v_mul_f32_e32 v89, v89, v89
	v_mul_f32_e32 v90, v90, v90
	v_mul_f32_e32 v91, v91, v91
	v_cvt_pk_bf16_f32 v88, v92, v88
	v_pk_mul_f32 v[86:87], v[170:171], v[86:87] op_sel_hi:[0,1]
	v_pk_mul_f32 v[84:85], v[170:171], v[84:85] op_sel_hi:[0,1]
	v_max_f32_e32 v80, 0, v80
	v_max_f32_e32 v81, 0, v81
	v_max_f32_e32 v82, 0, v82
	v_lshl_add_u64 v[96:97], v[174:175], 0, v[96:97]
	v_cvt_pk_bf16_f32 v89, v89, v90
	v_cvt_pk_bf16_f32 v90, v98, v93
	v_cvt_pk_bf16_f32 v91, v94, v91
	v_max_f32_e32 v84, 0, v84
	global_store_dwordx4 v[96:97], v[88:91], off sc1
	s_nop 1
	v_mul_f32_e32 v88, v80, v80
	v_max_f32_e32 v80, 0, v85
	v_mul_f32_e32 v85, v81, v81
	v_max_f32_e32 v81, 0, v86
	v_mul_f32_e32 v86, v82, v82
	v_max_f32_e32 v82, 0, v87
	v_mul_f32_e32 v80, v80, v80
	v_mul_f32_e32 v81, v81, v81
	v_max_f32_e32 v83, 0, v83
	v_mul_f32_e32 v82, v82, v82
	v_pk_mul_f32 v[72:73], v[154:155], v[72:73] op_sel_hi:[0,1]
	v_mul_f32_e32 v84, v84, v84
	v_mul_f32_e32 v83, v83, v83
	v_cvt_pk_bf16_f32 v80, v84, v80
	v_cvt_pk_bf16_f32 v81, v81, v82
	v_cvt_pk_bf16_f32 v82, v88, v85
	v_pk_mul_f32 v[76:77], v[154:155], v[76:77] op_sel_hi:[0,1]
	v_pk_mul_f32 v[74:75], v[154:155], v[74:75] op_sel_hi:[0,1]
	v_max_f32_e32 v72, 0, v72
	v_cvt_pk_bf16_f32 v83, v86, v83
	v_lshl_add_u64 v[84:85], v[96:97], 0, s[22:23]
	global_store_dwordx4 v[84:85], v[80:83], off sc1
	s_nop 1
	v_or_b32_e32 v80, 48, v172
	v_pk_mul_f32 v[78:79], v[154:155], v[78:79] op_sel_hi:[0,1]
	v_mul_f32_e32 v82, v72, v72
	v_max_f32_e32 v72, 0, v77
	v_max_f32_e32 v73, 0, v73
	v_max_f32_e32 v74, 0, v74
	v_ashrrev_i32_e32 v81, 31, v80
	v_max_f32_e32 v76, 0, v76
	v_mul_f32_e32 v72, v72, v72
	v_mul_f32_e32 v77, v73, v73
	v_max_f32_e32 v73, 0, v78
	v_mul_f32_e32 v78, v74, v74
	v_max_f32_e32 v74, 0, v79
	v_max_f32_e32 v75, 0, v75
	v_pk_mul_f32 v[66:67], v[154:155], v[66:67] op_sel_hi:[0,1]
	v_pk_mul_f32 v[64:65], v[154:155], v[64:65] op_sel_hi:[0,1]
	v_lshlrev_b64 v[80:81], 14, v[80:81]
	v_mul_f32_e32 v76, v76, v76
	v_mul_f32_e32 v73, v73, v73
	v_mul_f32_e32 v74, v74, v74
	v_mul_f32_e32 v75, v75, v75
	v_cvt_pk_bf16_f32 v72, v76, v72
	v_pk_mul_f32 v[70:71], v[154:155], v[70:71] op_sel_hi:[0,1]
	v_pk_mul_f32 v[68:69], v[154:155], v[68:69] op_sel_hi:[0,1]
	v_max_f32_e32 v64, 0, v64
	v_max_f32_e32 v65, 0, v65
	v_max_f32_e32 v66, 0, v66
	v_lshl_add_u64 v[80:81], v[174:175], 0, v[80:81]
	v_cvt_pk_bf16_f32 v73, v73, v74
	v_cvt_pk_bf16_f32 v74, v82, v77
	v_cvt_pk_bf16_f32 v75, v78, v75
	v_max_f32_e32 v68, 0, v68
	global_store_dwordx4 v[80:81], v[72:75], off sc1
	s_nop 1
	v_mul_f32_e32 v72, v64, v64
	v_max_f32_e32 v64, 0, v69
	v_mul_f32_e32 v69, v65, v65
	v_max_f32_e32 v65, 0, v70
	v_mul_f32_e32 v70, v66, v66
	v_max_f32_e32 v66, 0, v71
	v_mul_f32_e32 v64, v64, v64
	v_mul_f32_e32 v65, v65, v65
	v_max_f32_e32 v67, 0, v67
	v_mul_f32_e32 v66, v66, v66
	v_pk_mul_f32 v[56:57], v[152:153], v[56:57] op_sel_hi:[0,1]
	v_mul_f32_e32 v68, v68, v68
	v_mul_f32_e32 v67, v67, v67
	v_cvt_pk_bf16_f32 v64, v68, v64
	v_cvt_pk_bf16_f32 v65, v65, v66
	v_cvt_pk_bf16_f32 v66, v72, v69
	v_pk_mul_f32 v[60:61], v[152:153], v[60:61] op_sel_hi:[0,1]
	v_pk_mul_f32 v[58:59], v[152:153], v[58:59] op_sel_hi:[0,1]
	v_max_f32_e32 v56, 0, v56
	v_cvt_pk_bf16_f32 v67, v70, v67
	v_lshl_add_u64 v[68:69], v[80:81], 0, s[22:23]
	global_store_dwordx4 v[68:69], v[64:67], off sc1
	s_nop 1
	v_pk_mul_f32 v[62:63], v[152:153], v[62:63] op_sel_hi:[0,1]
	v_mul_f32_e32 v66, v56, v56
	v_max_f32_e32 v56, 0, v61
	v_max_f32_e32 v57, 0, v57
	v_max_f32_e32 v58, 0, v58
	v_max_f32_e32 v60, 0, v60
	v_mul_f32_e32 v56, v56, v56
	v_mul_f32_e32 v61, v57, v57
	v_max_f32_e32 v57, 0, v62
	v_mul_f32_e32 v62, v58, v58
	v_max_f32_e32 v58, 0, v63
	v_max_f32_e32 v59, 0, v59
	v_pk_mul_f32 v[50:51], v[152:153], v[50:51] op_sel_hi:[0,1]
	v_pk_mul_f32 v[48:49], v[152:153], v[48:49] op_sel_hi:[0,1]
	v_mul_f32_e32 v60, v60, v60
	v_mul_f32_e32 v57, v57, v57
	v_mul_f32_e32 v58, v58, v58
	v_mul_f32_e32 v59, v59, v59
	v_cvt_pk_bf16_f32 v56, v60, v56
	v_pk_mul_f32 v[54:55], v[152:153], v[54:55] op_sel_hi:[0,1]
; __device__ __forceinline__ unsigned cvt_pk_bf16(float lo, float hi) { unsigned r; asm volatile("v_cvt_pk_bf16_f32 %0, %1, %2" : "=v"(r) : "v"(lo), "v"(hi)); return r; }
;     __device__ __forceinline__ void operator()(const f32x4 (&acc)[2][2][4][2], const Unit& u, int wr, int wc, int fr, int fq, int, const float (&rsv_)[8]) const {
;     ...
;             for (int m = 0; m < 4; ++m) { bf16_t* rowp = base + (size_t)(row0 + ai * HALF + m * 16) * ldc + col0;
;                 const float rs = rsv[ai][m];
; #pragma unroll
;                 for (int bj = 0; bj < 2; ++bj) { f32x4 v0 = acc[ai][bj][m][0] * rs, v1 = acc[ai][bj][m][1] * rs;
;                     if (ACT == 1) {
; #pragma unroll
;                         for (int j = 0; j < 4; ++j) { const float a = fmaxf(v0[j], 0.f), b = fmaxf(v1[j], 0.f); v0[j] = a * a; v1[j] = b * b; } }
;                     if (ACT == 2) { if (act2) {
; #pragma unroll
;                         for (int j = 0; j < 4; ++j) { float x = v0[j]; float z = 0.7978845608028654f * (x + 0.044715f * x * x * x); v0[j] = x / (1.f + __expf(-2.f * z));
;                                                       x = v1[j]; z = 0.7978845608028654f * (x + 0.044715f * x * x * x); v1[j] = x / (1.f + __expf(-2.f * z)); } } }
;                     u32x4 w; w.x = cvt_pk_bf16(v0[0], v0[1]); w.y = cvt_pk_bf16(v0[2], v0[3]); w.z = cvt_pk_bf16(v1[0], v1[1]); w.w = cvt_pk_bf16(v1[2], v1[3]);
;                     { u32x4* dp_ = (u32x4*)(rowp + bj * HALF); asm volatile("global_store_dwordx4 %0, %1, off sc1\n\ts_nop 1" :: "v"(dp_), "v"(w) : "memory"); } } }
	v_pk_mul_f32 v[52:53], v[152:153], v[52:53] op_sel_hi:[0,1]
	v_max_f32_e32 v48, 0, v48
	v_max_f32_e32 v49, 0, v49
	v_max_f32_e32 v50, 0, v50
	v_lshl_add_u64 v[64:65], v[144:145], 0, s[24:25]
	v_cvt_pk_bf16_f32 v57, v57, v58
	v_cvt_pk_bf16_f32 v58, v66, v61
	v_cvt_pk_bf16_f32 v59, v62, v59
	v_max_f32_e32 v52, 0, v52
	global_store_dwordx4 v[64:65], v[56:59], off sc1
	s_nop 1
	v_mul_f32_e32 v56, v48, v48
	v_max_f32_e32 v48, 0, v53
	v_mul_f32_e32 v53, v49, v49
	v_max_f32_e32 v49, 0, v54
	v_mul_f32_e32 v54, v50, v50
	v_max_f32_e32 v50, 0, v55
	v_mul_f32_e32 v48, v48, v48
	v_mul_f32_e32 v49, v49, v49
	v_max_f32_e32 v51, 0, v51
	v_mul_f32_e32 v50, v50, v50
	v_pk_mul_f32 v[40:41], v[150:151], v[40:41] op_sel_hi:[0,1]
	v_mul_f32_e32 v52, v52, v52
	v_mul_f32_e32 v51, v51, v51
	v_cvt_pk_bf16_f32 v48, v52, v48
	v_cvt_pk_bf16_f32 v49, v49, v50
	v_cvt_pk_bf16_f32 v50, v56, v53
	v_pk_mul_f32 v[44:45], v[150:151], v[44:45] op_sel_hi:[0,1]
	v_pk_mul_f32 v[42:43], v[150:151], v[42:43] op_sel_hi:[0,1]
	v_max_f32_e32 v40, 0, v40
	v_cvt_pk_bf16_f32 v51, v54, v51
	v_lshl_add_u64 v[52:53], v[144:145], 0, s[26:27]
	global_store_dwordx4 v[52:53], v[48:51], off sc1
	s_nop 1
	v_pk_mul_f32 v[46:47], v[150:151], v[46:47] op_sel_hi:[0,1]
	v_mul_f32_e32 v50, v40, v40
	v_max_f32_e32 v40, 0, v45
	v_max_f32_e32 v41, 0, v41
	v_max_f32_e32 v42, 0, v42
	v_max_f32_e32 v44, 0, v44
	v_mul_f32_e32 v40, v40, v40
	v_mul_f32_e32 v45, v41, v41
	v_max_f32_e32 v41, 0, v46
	v_mul_f32_e32 v46, v42, v42
	v_max_f32_e32 v42, 0, v47
	v_max_f32_e32 v43, 0, v43
	v_pk_mul_f32 v[34:35], v[150:151], v[34:35] op_sel_hi:[0,1]
	v_pk_mul_f32 v[32:33], v[150:151], v[32:33] op_sel_hi:[0,1]
	v_mul_f32_e32 v44, v44, v44
	v_mul_f32_e32 v41, v41, v41
	v_mul_f32_e32 v42, v42, v42
	v_mul_f32_e32 v43, v43, v43
	v_cvt_pk_bf16_f32 v40, v44, v40
	v_pk_mul_f32 v[38:39], v[150:151], v[38:39] op_sel_hi:[0,1]
	v_pk_mul_f32 v[36:37], v[150:151], v[36:37] op_sel_hi:[0,1]
	v_max_f32_e32 v32, 0, v32
	v_max_f32_e32 v33, 0, v33
	v_max_f32_e32 v34, 0, v34
	v_lshl_add_u64 v[48:49], v[144:145], 0, s[28:29]
	v_cvt_pk_bf16_f32 v41, v41, v42
	v_cvt_pk_bf16_f32 v42, v50, v45
	v_cvt_pk_bf16_f32 v43, v46, v43
	v_max_f32_e32 v36, 0, v36
	global_store_dwordx4 v[48:49], v[40:43], off sc1
	s_nop 1
	v_mul_f32_e32 v40, v32, v32
	v_max_f32_e32 v32, 0, v37
	v_mul_f32_e32 v37, v33, v33
	v_max_f32_e32 v33, 0, v38
	v_mul_f32_e32 v38, v34, v34
	v_max_f32_e32 v34, 0, v39
	v_mul_f32_e32 v32, v32, v32
	v_mul_f32_e32 v33, v33, v33
	v_max_f32_e32 v35, 0, v35
	v_mul_f32_e32 v34, v34, v34
	v_pk_mul_f32 v[24:25], v[148:149], v[24:25] op_sel_hi:[0,1]
	v_mul_f32_e32 v36, v36, v36
	v_mul_f32_e32 v35, v35, v35
	v_cvt_pk_bf16_f32 v32, v36, v32
	v_cvt_pk_bf16_f32 v33, v33, v34
	v_cvt_pk_bf16_f32 v34, v40, v37
	v_pk_mul_f32 v[28:29], v[148:149], v[28:29] op_sel_hi:[0,1]
	v_pk_mul_f32 v[26:27], v[148:149], v[26:27] op_sel_hi:[0,1]
	v_max_f32_e32 v24, 0, v24
	v_cvt_pk_bf16_f32 v35, v38, v35
	v_lshl_add_u64 v[36:37], v[144:145], 0, s[30:31]
	global_store_dwordx4 v[36:37], v[32:35], off sc1
	s_nop 1
	v_pk_mul_f32 v[30:31], v[148:149], v[30:31] op_sel_hi:[0,1]
	v_mul_f32_e32 v34, v24, v24
	v_max_f32_e32 v24, 0, v29
	v_max_f32_e32 v25, 0, v25
	v_max_f32_e32 v26, 0, v26
	v_max_f32_e32 v28, 0, v28
	v_mul_f32_e32 v24, v24, v24
	v_mul_f32_e32 v29, v25, v25
	v_max_f32_e32 v25, 0, v30
	v_mul_f32_e32 v30, v26, v26
	v_max_f32_e32 v26, 0, v31
	v_max_f32_e32 v27, 0, v27
	v_pk_mul_f32 v[18:19], v[148:149], v[18:19] op_sel_hi:[0,1]
	v_pk_mul_f32 v[16:17], v[148:149], v[16:17] op_sel_hi:[0,1]
	v_mul_f32_e32 v28, v28, v28
	v_mul_f32_e32 v25, v25, v25
	v_mul_f32_e32 v26, v26, v26
	v_mul_f32_e32 v27, v27, v27
	v_cvt_pk_bf16_f32 v24, v28, v24
	v_pk_mul_f32 v[22:23], v[148:149], v[22:23] op_sel_hi:[0,1]
	v_pk_mul_f32 v[20:21], v[148:149], v[20:21] op_sel_hi:[0,1]
	v_max_f32_e32 v16, 0, v16
	v_max_f32_e32 v17, 0, v17
	v_max_f32_e32 v18, 0, v18
	v_lshl_add_u64 v[32:33], v[144:145], 0, s[34:35]
	v_cvt_pk_bf16_f32 v25, v25, v26
	v_cvt_pk_bf16_f32 v26, v34, v29
	v_cvt_pk_bf16_f32 v27, v30, v27
	v_max_f32_e32 v20, 0, v20
	global_store_dwordx4 v[32:33], v[24:27], off sc1
	s_nop 1
	v_mul_f32_e32 v24, v16, v16
	v_max_f32_e32 v16, 0, v21
	v_mul_f32_e32 v21, v17, v17
	v_max_f32_e32 v17, 0, v22
	v_mul_f32_e32 v22, v18, v18
	v_max_f32_e32 v18, 0, v23
	v_mul_f32_e32 v16, v16, v16
	v_mul_f32_e32 v17, v17, v17
	v_max_f32_e32 v19, 0, v19
	v_mul_f32_e32 v18, v18, v18
	v_pk_mul_f32 v[8:9], v[146:147], v[8:9] op_sel_hi:[0,1]
	v_mul_f32_e32 v20, v20, v20
	v_mul_f32_e32 v19, v19, v19
	v_cvt_pk_bf16_f32 v16, v20, v16
	v_cvt_pk_bf16_f32 v17, v17, v18
	v_cvt_pk_bf16_f32 v18, v24, v21
	v_pk_mul_f32 v[12:13], v[146:147], v[12:13] op_sel_hi:[0,1]
	v_pk_mul_f32 v[10:11], v[146:147], v[10:11] op_sel_hi:[0,1]
	v_max_f32_e32 v8, 0, v8
	v_cvt_pk_bf16_f32 v19, v22, v19
	v_lshl_add_u64 v[20:21], v[144:145], 0, s[36:37]
	global_store_dwordx4 v[20:21], v[16:19], off sc1
	s_nop 1
	v_pk_mul_f32 v[14:15], v[146:147], v[14:15] op_sel_hi:[0,1]
	v_mul_f32_e32 v18, v8, v8
	v_max_f32_e32 v8, 0, v13
	v_max_f32_e32 v9, 0, v9
	v_max_f32_e32 v10, 0, v10
	v_max_f32_e32 v12, 0, v12
	v_mul_f32_e32 v8, v8, v8
	v_mul_f32_e32 v13, v9, v9
	v_max_f32_e32 v9, 0, v14
	v_mul_f32_e32 v14, v10, v10
	v_max_f32_e32 v10, 0, v15
	v_max_f32_e32 v11, 0, v11
	v_pk_mul_f32 v[2:3], v[146:147], v[2:3] op_sel_hi:[0,1]
	v_pk_mul_f32 v[0:1], v[146:147], v[0:1] op_sel_hi:[0,1]
	v_mul_f32_e32 v12, v12, v12
	v_mul_f32_e32 v9, v9, v9
	v_mul_f32_e32 v10, v10, v10
	v_mul_f32_e32 v11, v11, v11
	v_cvt_pk_bf16_f32 v8, v12, v8
	v_pk_mul_f32 v[6:7], v[146:147], v[6:7] op_sel_hi:[0,1]
	v_pk_mul_f32 v[4:5], v[146:147], v[4:5] op_sel_hi:[0,1]
	v_max_f32_e32 v0, 0, v0
	v_max_f32_e32 v1, 0, v1
	v_max_f32_e32 v2, 0, v2
	v_lshl_add_u64 v[16:17], v[144:145], 0, s[40:41]
	v_cvt_pk_bf16_f32 v9, v9, v10
	v_cvt_pk_bf16_f32 v10, v18, v13
	v_cvt_pk_bf16_f32 v11, v14, v11
	v_max_f32_e32 v4, 0, v4
	global_store_dwordx4 v[16:17], v[8:11], off sc1
	s_nop 1
	v_mul_f32_e32 v8, v0, v0
	v_max_f32_e32 v0, 0, v5
	v_mul_f32_e32 v5, v1, v1
	v_max_f32_e32 v1, 0, v6
	v_mul_f32_e32 v6, v2, v2
	v_max_f32_e32 v2, 0, v7
	v_max_f32_e32 v3, 0, v3
	v_mul_f32_e32 v4, v4, v4
	v_mul_f32_e32 v0, v0, v0
	v_mul_f32_e32 v1, v1, v1
	v_mul_f32_e32 v2, v2, v2
	v_mul_f32_e32 v3, v3, v3
	v_cvt_pk_bf16_f32 v0, v4, v0
	v_cvt_pk_bf16_f32 v1, v1, v2
	v_cvt_pk_bf16_f32 v2, v8, v5
	v_cvt_pk_bf16_f32 v3, v6, v3
	v_lshl_add_u64 v[4:5], v[144:145], 0, s[42:43]
	global_store_dwordx4 v[4:5], v[0:3], off sc1
	s_nop 1
	s_and_b64 vcc, exec, s[6:7]
	s_mov_b64 s[4:5], -1
	s_cbranch_vccnz .LBB0_918
	s_andn2_b64 vcc, exec, s[14:15]
	s_cbranch_vccnz .LBB0_917
	s_barrier
	s_branch .LBB0_917

; template <class Epi, bool ALIGN_EPI>
; __device__ __forceinline__ void gemm_phase(LAS unsigned char* lds, const Gemm g, const StaticOrder& S, const Epi& E) {
;     ...
;         cur = nxt; cA = nA; cB = nB; ++ui;
; #pragma unroll
;         for (int i_ = 0; i_ < 8; ++i_) rsv[i_] = rsn[i_];
.LBB0_1090:
	s_waitcnt vmcnt(16)
	s_andn2_b64 vcc, exec, s[4:5]
	v_mov_b32_e32 v165, v157
	v_mov_b32_e32 v166, v158
	v_mov_b32_e32 v167, v159
	v_mov_b32_e32 v169, v160
	v_mov_b32_e32 v170, v161
	v_mov_b32_e32 v171, v162
	v_mov_b32_e32 v172, v163
	v_mov_b32_e32 v144, v164
	s_mov_b32 s42, s26
	s_mov_b32 s40, s28
	s_mov_b64 s[36:37], s[34:35]
	s_mov_b64 s[4:5], s[30:31]
	s_cbranch_vccz .LBB0_1141

; __device__ __forceinline__ unsigned cvt_pk_bf16(float lo, float hi) { unsigned r; asm volatile("v_cvt_pk_bf16_f32 %0, %1, %2" : "=v"(r) : "v"(lo), "v"(hi)); return r; }
;     __device__ __forceinline__ void operator()(const f32x4 (&acc)[2][2][4][2], const Unit& u, int wr, int wc, int fr, int fq, int, const float (&rsv_)[8]) const {
;     ...
;         float rsv[2][4];
; #pragma unroll
;         for (int ai = 0; ai < 2; ++ai)
; #pragma unroll
;             for (int m = 0; m < 4; ++m) rsv[ai][m] = ss ? rsqrtf(rsv_[ai * 4 + m] * (1.f / 2048.f) + EPS) : 1.f;
; #pragma unroll
;         for (int ai = 0; ai < 2; ++ai)
; #pragma unroll
;             for (int m = 0; m < 4; ++m) { bf16_t* rowp = base + (size_t)(row0 + ai * HALF + m * 16) * ldc + col0;
;                 const float rs = rsv[ai][m];
; #pragma unroll
;                 for (int bj = 0; bj < 2; ++bj) { f32x4 v0 = acc[ai][bj][m][0] * rs, v1 = acc[ai][bj][m][1] * rs;
;                     if (ACT == 1) {
; #pragma unroll
;                         for (int j = 0; j < 4; ++j) { const float a = fmaxf(v0[j], 0.f), b = fmaxf(v1[j], 0.f); v0[j] = a * a; v1[j] = b * b; } }
;                     if (ACT == 2) { if (act2) {
; #pragma unroll
;                         for (int j = 0; j < 4; ++j) { float x = v0[j]; float z = 0.7978845608028654f * (x + 0.044715f * x * x * x); v0[j] = x / (1.f + __expf(-2.f * z));
;                                                       x = v1[j]; z = 0.7978845608028654f * (x + 0.044715f * x * x * x); v1[j] = x / (1.f + __expf(-2.f * z)); } } }
;                     u32x4 w; w.x = cvt_pk_bf16(v0[0], v0[1]); w.y = cvt_pk_bf16(v0[2], v0[3]); w.z = cvt_pk_bf16(v1[0], v1[1]); w.w = cvt_pk_bf16(v1[2], v1[3]);
.LBB0_1106:
	s_waitcnt vmcnt(8)
	v_fmamk_f32 v144, v144, 0x3a000000, v156
	v_mul_f32_e32 v145, 0x4b800000, v144
	v_cmp_gt_f32_e32 vcc, s63, v144
	s_nop 1
	v_cndmask_b32_e32 v144, v144, v145, vcc
	v_rsq_f32_e32 v144, v144
	s_nop 0
	v_mul_f32_e32 v145, 0x45800000, v144
	v_cndmask_b32_e32 v144, v144, v145, vcc
	v_pk_mul_f32 v[146:147], v[144:145], v[124:125] op_sel_hi:[0,1]
	v_pk_mul_f32 v[124:125], v[144:145], v[122:123] op_sel_hi:[0,1]
	v_cndmask_b32_e64 v122, 0, 1, s[46:47]
	v_pk_mul_f32 v[126:127], v[144:145], v[126:127] op_sel_hi:[0,1]
	v_cmp_ne_u32_e64 s[6:7], 1, v122
	s_andn2_b64 vcc, exec, s[46:47]
	v_pk_mul_f32 v[148:149], v[144:145], v[120:121] op_sel_hi:[0,1]
	s_cbranch_vccnz .LBB0_1108
	v_mul_f32_e32 v145, 0x3d372713, v126
	v_mul_f32_e32 v168, 0x3d372713, v127
	v_mul_f32_e32 v145, v126, v145
	v_mul_f32_e32 v168, v127, v168
	v_fma_f32 v145, v126, v145, v126
	v_fma_f32 v168, v127, v168, v127
	v_mul_f32_e32 v145, 0x3f4c422a, v145
	v_mul_f32_e32 v168, 0x3f4c422a, v168
	v_mul_f32_e32 v145, -2.0, v145
	v_mul_f32_e32 v168, -2.0, v168
	v_mul_f32_e32 v145, 0x3fb8aa3b, v145
	v_mul_f32_e32 v168, 0x3fb8aa3b, v168
	v_exp_f32_e32 v174, v145
	v_exp_f32_e32 v175, v168
	v_mul_f32_e32 v145, 0x3d372713, v124
	v_mul_f32_e32 v145, v124, v145
	v_fma_f32 v145, v124, v145, v124
	v_pk_add_f32 v[174:175], v[174:175], 1.0 op_sel_hi:[1,0]
	v_mul_f32_e32 v145, 0x3f4c422a, v145
	v_div_scale_f32 v168, s[0:1], v175, v175, v127
	v_rcp_f32_e32 v173, v168
	v_mul_f32_e32 v121, 0x3d372713, v148
	v_mul_f32_e32 v145, -2.0, v145
	v_mul_f32_e32 v121, v148, v121
	v_mul_f32_e32 v145, 0x3fb8aa3b, v145
	v_fma_f32 v121, v148, v121, v148
	v_exp_f32_e32 v176, v145
	v_fma_f32 v145, -v168, v173, 1.0
	v_mul_f32_e32 v121, 0x3f4c422a, v121
	v_fmac_f32_e32 v173, v145, v173
	v_div_scale_f32 v145, vcc, v127, v175, v127
	v_mul_f32_e32 v121, -2.0, v121
	v_mul_f32_e32 v177, v145, v173
	v_mul_f32_e32 v121, 0x3fb8aa3b, v121
	v_fma_f32 v178, -v168, v177, v145
	v_mul_f32_e32 v120, 0x3d372713, v146
	v_exp_f32_e32 v122, v121
	v_mul_f32_e32 v121, 0x3d372713, v147
	v_fmac_f32_e32 v177, v178, v173
	v_mul_f32_e32 v120, v146, v120
	v_mul_f32_e32 v121, v147, v121
	v_fma_f32 v145, -v168, v177, v145
	v_div_scale_f32 v168, s[0:1], v174, v174, v126
	v_fma_f32 v120, v146, v120, v146
	v_fma_f32 v121, v147, v121, v147
	v_rcp_f32_e32 v178, v168
	v_mul_f32_e32 v120, 0x3f4c422a, v120
	v_mul_f32_e32 v121, 0x3f4c422a, v121
	v_mul_f32_e32 v120, -2.0, v120
	v_mul_f32_e32 v121, -2.0, v121
	v_mul_f32_e32 v120, 0x3fb8aa3b, v120
	v_mul_f32_e32 v121, 0x3fb8aa3b, v121
	v_div_fmas_f32 v145, v145, v173, v177
	v_exp_f32_e32 v120, v120
	v_exp_f32_e32 v121, v121
	v_div_fixup_f32 v127, v145, v175, v127
	v_fma_f32 v145, -v168, v178, 1.0
	v_fmac_f32_e32 v178, v145, v178
	v_div_scale_f32 v145, vcc, v126, v174, v126
	v_mul_f32_e32 v173, v145, v178
	v_fma_f32 v175, -v168, v173, v145
	v_pk_add_f32 v[120:121], v[120:121], 1.0 op_sel_hi:[1,0]
	v_fmac_f32_e32 v173, v175, v178
	v_fma_f32 v145, -v168, v173, v145
	v_div_scale_f32 v168, s[0:1], v121, v121, v147
	v_rcp_f32_e32 v175, v168
	v_div_fmas_f32 v145, v145, v178, v173
	v_div_fixup_f32 v126, v145, v174, v126
	v_mul_f32_e32 v123, 0x3d372713, v149
	v_fma_f32 v145, -v168, v175, 1.0
	v_fmac_f32_e32 v175, v145, v175
	v_div_scale_f32 v145, vcc, v147, v121, v147
	v_mul_f32_e32 v173, v145, v175
	v_fma_f32 v174, -v168, v173, v145
	v_fmac_f32_e32 v173, v174, v175
	v_fma_f32 v145, -v168, v173, v145
	v_div_fmas_f32 v145, v145, v175, v173
	v_mul_f32_e32 v173, 0x3d372713, v125
	v_div_scale_f32 v168, s[0:1], v120, v120, v146
	v_mul_f32_e32 v173, v125, v173
	v_rcp_f32_e32 v178, v168
	v_fma_f32 v173, v125, v173, v125
	v_mul_f32_e32 v173, 0x3f4c422a, v173
	v_mul_f32_e32 v173, -2.0, v173
	v_mul_f32_e32 v173, 0x3fb8aa3b, v173
	v_div_fixup_f32 v147, v145, v121, v147
	v_fma_f32 v121, -v168, v178, 1.0
	v_exp_f32_e32 v177, v173
	v_mul_f32_e32 v123, v149, v123
	v_fmac_f32_e32 v178, v121, v178
	v_div_scale_f32 v121, vcc, v146, v120, v146
	v_fma_f32 v123, v149, v123, v149
	v_mul_f32_e32 v145, v121, v178
	v_mul_f32_e32 v123, 0x3f4c422a, v123
	v_fma_f32 v173, -v168, v145, v121
	v_mul_f32_e32 v123, -2.0, v123
	v_fmac_f32_e32 v145, v173, v178
	v_pk_add_f32 v[174:175], v[176:177], 1.0 op_sel_hi:[1,0]
	v_mul_f32_e32 v123, 0x3fb8aa3b, v123
	v_fma_f32 v121, -v168, v145, v121
	v_div_scale_f32 v168, s[0:1], v175, v175, v125
	v_exp_f32_e32 v123, v123
	v_rcp_f32_e32 v173, v168
	v_div_fmas_f32 v121, v121, v178, v145
	v_div_fixup_f32 v146, v121, v120, v146
	v_pk_add_f32 v[120:121], v[122:123], 1.0 op_sel_hi:[1,0]
	v_fma_f32 v122, -v168, v173, 1.0
	v_fmac_f32_e32 v173, v122, v173
	v_div_scale_f32 v122, vcc, v125, v175, v125
	v_mul_f32_e32 v123, v122, v173
	v_fma_f32 v145, -v168, v123, v122
	v_fmac_f32_e32 v123, v145, v173
	v_div_scale_f32 v145, s[0:1], v174, v174, v124
	v_fma_f32 v122, -v168, v123, v122
	v_rcp_f32_e32 v168, v145
	v_div_fmas_f32 v122, v122, v173, v123
	v_div_fixup_f32 v125, v122, v175, v125
	v_fma_f32 v122, -v145, v168, 1.0
	v_fmac_f32_e32 v168, v122, v168
	v_div_scale_f32 v122, vcc, v124, v174, v124
	v_mul_f32_e32 v123, v122, v168
	v_fma_f32 v173, -v145, v123, v122
	v_fmac_f32_e32 v123, v173, v168
	v_fma_f32 v122, -v145, v123, v122
	v_div_scale_f32 v145, s[0:1], v121, v121, v149
	v_rcp_f32_e32 v173, v145
	v_div_fmas_f32 v122, v122, v168, v123
	v_div_fixup_f32 v124, v122, v174, v124
	v_fma_f32 v122, -v145, v173, 1.0
	v_fmac_f32_e32 v173, v122, v173
	v_div_scale_f32 v122, vcc, v149, v121, v149
	v_mul_f32_e32 v123, v122, v173
	v_fma_f32 v168, -v145, v123, v122
	v_fmac_f32_e32 v123, v168, v173
	v_fma_f32 v122, -v145, v123, v122
	v_div_scale_f32 v145, s[0:1], v120, v120, v148
	v_rcp_f32_e32 v168, v145
	v_div_fmas_f32 v122, v122, v173, v123
	v_div_fixup_f32 v149, v122, v121, v149
	v_fma_f32 v121, -v145, v168, 1.0
	v_fmac_f32_e32 v168, v121, v168
	v_div_scale_f32 v121, vcc, v148, v120, v148
	v_mul_f32_e32 v122, v121, v168
	v_fma_f32 v123, -v145, v122, v121
	v_fmac_f32_e32 v122, v123, v168
	v_fma_f32 v121, -v145, v122, v121
	v_div_fmas_f32 v121, v121, v168, v122
	v_div_fixup_f32 v148, v121, v120, v148
